# combo1 + adaLN coefficient-table init loops: 24 loads batched, single wait (was 2 waits per iteration)
# speedup vs baseline: 1.0013x; 1.0013x over previous
.LBB0_143:
	v_lshrrev_b32_e32 v85, 11, v1
	v_and_b32_e32 v86, 0x7ff, v1
	v_lshlrev_b32_e32 v86, 2, v86
	v_mul_u32_u24_e32 v87, 0x12000, v85
	v_add_u32_e32 v87, v87, v86
	v_add_u32_e32 v88, s24, v87
	global_load_dword v60, v88, s[12:13]
	global_load_dword v62, v86, s[4:5]
	global_load_dword v61, v87, s[12:13]
	v_add_u32_e32 v84, 0x200, v1
	v_lshrrev_b32_e32 v85, 11, v84
	v_and_b32_e32 v86, 0x7ff, v84
	v_lshlrev_b32_e32 v86, 2, v86
	v_mul_u32_u24_e32 v87, 0x12000, v85
	v_add_u32_e32 v87, v87, v86
	v_add_u32_e32 v88, s24, v87
	global_load_dword v63, v88, s[12:13]
	global_load_dword v65, v86, s[4:5]
	global_load_dword v64, v87, s[12:13]
	v_add_u32_e32 v84, 0x400, v1
	v_lshrrev_b32_e32 v85, 11, v84
	v_and_b32_e32 v86, 0x7ff, v84
	v_lshlrev_b32_e32 v86, 2, v86
	v_mul_u32_u24_e32 v87, 0x12000, v85
	v_add_u32_e32 v87, v87, v86
	v_add_u32_e32 v88, s24, v87
	global_load_dword v66, v88, s[12:13]
	global_load_dword v68, v86, s[4:5]
	global_load_dword v67, v87, s[12:13]
	v_add_u32_e32 v84, 0x600, v1
	v_lshrrev_b32_e32 v85, 11, v84
	v_and_b32_e32 v86, 0x7ff, v84
	v_lshlrev_b32_e32 v86, 2, v86
	v_mul_u32_u24_e32 v87, 0x12000, v85
	v_add_u32_e32 v87, v87, v86
	v_add_u32_e32 v88, s24, v87
	global_load_dword v69, v88, s[12:13]
	global_load_dword v71, v86, s[4:5]
	global_load_dword v70, v87, s[12:13]
	v_add_u32_e32 v84, 0x800, v1
	v_lshrrev_b32_e32 v85, 11, v84
	v_and_b32_e32 v86, 0x7ff, v84
	v_lshlrev_b32_e32 v86, 2, v86
	v_mul_u32_u24_e32 v87, 0x12000, v85
	v_add_u32_e32 v87, v87, v86
	v_add_u32_e32 v88, s24, v87
	global_load_dword v72, v88, s[12:13]
	global_load_dword v74, v86, s[4:5]
	global_load_dword v73, v87, s[12:13]
	v_add_u32_e32 v84, 0xa00, v1
	v_lshrrev_b32_e32 v85, 11, v84
	v_and_b32_e32 v86, 0x7ff, v84
	v_lshlrev_b32_e32 v86, 2, v86
	v_mul_u32_u24_e32 v87, 0x12000, v85
	v_add_u32_e32 v87, v87, v86
	v_add_u32_e32 v88, s24, v87
	global_load_dword v75, v88, s[12:13]
	global_load_dword v77, v86, s[4:5]
	global_load_dword v76, v87, s[12:13]
	v_add_u32_e32 v84, 0xc00, v1
	v_lshrrev_b32_e32 v85, 11, v84
	v_and_b32_e32 v86, 0x7ff, v84
	v_lshlrev_b32_e32 v86, 2, v86
	v_mul_u32_u24_e32 v87, 0x12000, v85
	v_add_u32_e32 v87, v87, v86
	v_add_u32_e32 v88, s24, v87
	global_load_dword v78, v88, s[12:13]
	global_load_dword v80, v86, s[4:5]
	global_load_dword v79, v87, s[12:13]
	v_add_u32_e32 v84, 0xe00, v1
	v_lshrrev_b32_e32 v85, 11, v84
	v_and_b32_e32 v86, 0x7ff, v84
	v_lshlrev_b32_e32 v86, 2, v86
	v_mul_u32_u24_e32 v87, 0x12000, v85
	v_add_u32_e32 v87, v87, v86
	v_add_u32_e32 v88, s24, v87
	global_load_dword v81, v88, s[12:13]
	global_load_dword v83, v86, s[4:5]
	global_load_dword v82, v87, s[12:13]
	s_waitcnt vmcnt(0)
	v_add_f32_e32 v60, 1.0, v60
	v_mul_f32_e32 v60, v62, v60
	ds_write_b32 v0, v60
	ds_write_b32 v0, v61 offset:16384
	v_add_f32_e32 v63, 1.0, v63
	v_mul_f32_e32 v63, v65, v63
	ds_write_b32 v0, v63 offset:2048
	ds_write_b32 v0, v64 offset:18432
	v_add_f32_e32 v66, 1.0, v66
	v_mul_f32_e32 v66, v68, v66
	ds_write_b32 v0, v66 offset:4096
	ds_write_b32 v0, v67 offset:20480
	v_add_f32_e32 v69, 1.0, v69
	v_mul_f32_e32 v69, v71, v69
	ds_write_b32 v0, v69 offset:6144
	ds_write_b32 v0, v70 offset:22528
	v_add_f32_e32 v72, 1.0, v72
	v_mul_f32_e32 v72, v74, v72
	ds_write_b32 v0, v72 offset:8192
	ds_write_b32 v0, v73 offset:24576
	v_add_f32_e32 v75, 1.0, v75
	v_mul_f32_e32 v75, v77, v75
	ds_write_b32 v0, v75 offset:10240
	ds_write_b32 v0, v76 offset:26624
	v_add_f32_e32 v78, 1.0, v78
	v_mul_f32_e32 v78, v80, v78
	ds_write_b32 v0, v78 offset:12288
	ds_write_b32 v0, v79 offset:28672
	v_add_f32_e32 v81, 1.0, v81
	v_mul_f32_e32 v81, v83, v81
	ds_write_b32 v0, v81 offset:14336
	ds_write_b32 v0, v82 offset:30720
	v_add_u32_e32 v1, 0x1000, v1
	v_add_u32_e32 v0, 0x4000, v0
	s_mov_b64 s[20:21], exec

.LBB0_152:
	v_lshrrev_b32_e32 v85, 11, v17
	v_and_b32_e32 v86, 0x7ff, v17
	v_lshlrev_b32_e32 v86, 2, v86
	v_mul_u32_u24_e32 v87, 0x12000, v85
	v_add_u32_e32 v87, v87, v86
	v_add_u32_e32 v88, s24, v87
	global_load_dword v60, v88, s[12:13]
	global_load_dword v62, v86, s[2:3]
	global_load_dword v61, v87, s[12:13]
	v_add_u32_e32 v84, 0x200, v17
	v_lshrrev_b32_e32 v85, 11, v84
	v_and_b32_e32 v86, 0x7ff, v84
	v_lshlrev_b32_e32 v86, 2, v86
	v_mul_u32_u24_e32 v87, 0x12000, v85
	v_add_u32_e32 v87, v87, v86
	v_add_u32_e32 v88, s24, v87
	global_load_dword v63, v88, s[12:13]
	global_load_dword v65, v86, s[2:3]
	global_load_dword v64, v87, s[12:13]
	v_add_u32_e32 v84, 0x400, v17
	v_lshrrev_b32_e32 v85, 11, v84
	v_and_b32_e32 v86, 0x7ff, v84
	v_lshlrev_b32_e32 v86, 2, v86
	v_mul_u32_u24_e32 v87, 0x12000, v85
	v_add_u32_e32 v87, v87, v86
	v_add_u32_e32 v88, s24, v87
	global_load_dword v66, v88, s[12:13]
	global_load_dword v68, v86, s[2:3]
	global_load_dword v67, v87, s[12:13]
	v_add_u32_e32 v84, 0x600, v17
	v_lshrrev_b32_e32 v85, 11, v84
	v_and_b32_e32 v86, 0x7ff, v84
	v_lshlrev_b32_e32 v86, 2, v86
	v_mul_u32_u24_e32 v87, 0x12000, v85
	v_add_u32_e32 v87, v87, v86
	v_add_u32_e32 v88, s24, v87
	global_load_dword v69, v88, s[12:13]
	global_load_dword v71, v86, s[2:3]
	global_load_dword v70, v87, s[12:13]
	v_add_u32_e32 v84, 0x800, v17
	v_lshrrev_b32_e32 v85, 11, v84
	v_and_b32_e32 v86, 0x7ff, v84
	v_lshlrev_b32_e32 v86, 2, v86
	v_mul_u32_u24_e32 v87, 0x12000, v85
	v_add_u32_e32 v87, v87, v86
	v_add_u32_e32 v88, s24, v87
	global_load_dword v72, v88, s[12:13]
	global_load_dword v74, v86, s[2:3]
	global_load_dword v73, v87, s[12:13]
	v_add_u32_e32 v84, 0xa00, v17
	v_lshrrev_b32_e32 v85, 11, v84
	v_and_b32_e32 v86, 0x7ff, v84
	v_lshlrev_b32_e32 v86, 2, v86
	v_mul_u32_u24_e32 v87, 0x12000, v85
	v_add_u32_e32 v87, v87, v86
	v_add_u32_e32 v88, s24, v87
	global_load_dword v75, v88, s[12:13]
	global_load_dword v77, v86, s[2:3]
	global_load_dword v76, v87, s[12:13]
	v_add_u32_e32 v84, 0xc00, v17
	v_lshrrev_b32_e32 v85, 11, v84
	v_and_b32_e32 v86, 0x7ff, v84
	v_lshlrev_b32_e32 v86, 2, v86
	v_mul_u32_u24_e32 v87, 0x12000, v85
	v_add_u32_e32 v87, v87, v86
	v_add_u32_e32 v88, s24, v87
	global_load_dword v78, v88, s[12:13]
	global_load_dword v80, v86, s[2:3]
	global_load_dword v79, v87, s[12:13]
	v_add_u32_e32 v84, 0xe00, v17
	v_lshrrev_b32_e32 v85, 11, v84
	v_and_b32_e32 v86, 0x7ff, v84
	v_lshlrev_b32_e32 v86, 2, v86
	v_mul_u32_u24_e32 v87, 0x12000, v85
	v_add_u32_e32 v87, v87, v86
	v_add_u32_e32 v88, s24, v87
	global_load_dword v81, v88, s[12:13]
	global_load_dword v83, v86, s[2:3]
	global_load_dword v82, v87, s[12:13]
	s_waitcnt vmcnt(0)
	v_add_f32_e32 v60, 1.0, v60
	v_mul_f32_e32 v60, v62, v60
	ds_write_b32 v0, v60
	ds_write_b32 v0, v61 offset:16384
	v_add_f32_e32 v63, 1.0, v63
	v_mul_f32_e32 v63, v65, v63
	ds_write_b32 v0, v63 offset:2048
	ds_write_b32 v0, v64 offset:18432
	v_add_f32_e32 v66, 1.0, v66
	v_mul_f32_e32 v66, v68, v66
	ds_write_b32 v0, v66 offset:4096
	ds_write_b32 v0, v67 offset:20480
	v_add_f32_e32 v69, 1.0, v69
	v_mul_f32_e32 v69, v71, v69
	ds_write_b32 v0, v69 offset:6144
	ds_write_b32 v0, v70 offset:22528
	v_add_f32_e32 v72, 1.0, v72
	v_mul_f32_e32 v72, v74, v72
	ds_write_b32 v0, v72 offset:8192
	ds_write_b32 v0, v73 offset:24576
	v_add_f32_e32 v75, 1.0, v75
	v_mul_f32_e32 v75, v77, v75
	ds_write_b32 v0, v75 offset:10240
	ds_write_b32 v0, v76 offset:26624
	v_add_f32_e32 v78, 1.0, v78
	v_mul_f32_e32 v78, v80, v78
	ds_write_b32 v0, v78 offset:12288
	ds_write_b32 v0, v79 offset:28672
	v_add_f32_e32 v81, 1.0, v81
	v_mul_f32_e32 v81, v83, v81
	ds_write_b32 v0, v81 offset:14336
	ds_write_b32 v0, v82 offset:30720
	v_add_u32_e32 v17, 0x1000, v17
	v_add_u32_e32 v0, 0x4000, v0
	s_mov_b64 s[20:21], exec

.LBB0_364:
	v_lshrrev_b32_e32 v85, 11, v1
	v_and_b32_e32 v86, 0x7ff, v1
	v_lshlrev_b32_e32 v86, 2, v86
	v_mul_u32_u24_e32 v87, 0x12000, v85
	v_add_u32_e32 v87, v87, v86
	v_add_u32_e32 v88, s22, v87
	global_load_dword v60, v88, s[12:13]
	global_load_dword v62, v86, s[4:5]
	global_load_dword v61, v87, s[12:13]
	v_add_u32_e32 v84, 0x200, v1
	v_lshrrev_b32_e32 v85, 11, v84
	v_and_b32_e32 v86, 0x7ff, v84
	v_lshlrev_b32_e32 v86, 2, v86
	v_mul_u32_u24_e32 v87, 0x12000, v85
	v_add_u32_e32 v87, v87, v86
	v_add_u32_e32 v88, s22, v87
	global_load_dword v63, v88, s[12:13]
	global_load_dword v65, v86, s[4:5]
	global_load_dword v64, v87, s[12:13]
	v_add_u32_e32 v84, 0x400, v1
	v_lshrrev_b32_e32 v85, 11, v84
	v_and_b32_e32 v86, 0x7ff, v84
	v_lshlrev_b32_e32 v86, 2, v86
	v_mul_u32_u24_e32 v87, 0x12000, v85
	v_add_u32_e32 v87, v87, v86
	v_add_u32_e32 v88, s22, v87
	global_load_dword v66, v88, s[12:13]
	global_load_dword v68, v86, s[4:5]
	global_load_dword v67, v87, s[12:13]
	v_add_u32_e32 v84, 0x600, v1
	v_lshrrev_b32_e32 v85, 11, v84
	v_and_b32_e32 v86, 0x7ff, v84
	v_lshlrev_b32_e32 v86, 2, v86
	v_mul_u32_u24_e32 v87, 0x12000, v85
	v_add_u32_e32 v87, v87, v86
	v_add_u32_e32 v88, s22, v87
	global_load_dword v69, v88, s[12:13]
	global_load_dword v71, v86, s[4:5]
	global_load_dword v70, v87, s[12:13]
	v_add_u32_e32 v84, 0x800, v1
	v_lshrrev_b32_e32 v85, 11, v84
	v_and_b32_e32 v86, 0x7ff, v84
	v_lshlrev_b32_e32 v86, 2, v86
	v_mul_u32_u24_e32 v87, 0x12000, v85
	v_add_u32_e32 v87, v87, v86
	v_add_u32_e32 v88, s22, v87
	global_load_dword v72, v88, s[12:13]
	global_load_dword v74, v86, s[4:5]
	global_load_dword v73, v87, s[12:13]
	v_add_u32_e32 v84, 0xa00, v1
	v_lshrrev_b32_e32 v85, 11, v84
	v_and_b32_e32 v86, 0x7ff, v84
	v_lshlrev_b32_e32 v86, 2, v86
	v_mul_u32_u24_e32 v87, 0x12000, v85
	v_add_u32_e32 v87, v87, v86
	v_add_u32_e32 v88, s22, v87
	global_load_dword v75, v88, s[12:13]
	global_load_dword v77, v86, s[4:5]
	global_load_dword v76, v87, s[12:13]
	v_add_u32_e32 v84, 0xc00, v1
	v_lshrrev_b32_e32 v85, 11, v84
	v_and_b32_e32 v86, 0x7ff, v84
	v_lshlrev_b32_e32 v86, 2, v86
	v_mul_u32_u24_e32 v87, 0x12000, v85
	v_add_u32_e32 v87, v87, v86
	v_add_u32_e32 v88, s22, v87
	global_load_dword v78, v88, s[12:13]
	global_load_dword v80, v86, s[4:5]
	global_load_dword v79, v87, s[12:13]
	v_add_u32_e32 v84, 0xe00, v1
	v_lshrrev_b32_e32 v85, 11, v84
	v_and_b32_e32 v86, 0x7ff, v84
	v_lshlrev_b32_e32 v86, 2, v86
	v_mul_u32_u24_e32 v87, 0x12000, v85
	v_add_u32_e32 v87, v87, v86
	v_add_u32_e32 v88, s22, v87
	global_load_dword v81, v88, s[12:13]
	global_load_dword v83, v86, s[4:5]
	global_load_dword v82, v87, s[12:13]
	s_waitcnt vmcnt(0)
	v_add_f32_e32 v60, 1.0, v60
	v_mul_f32_e32 v60, v62, v60
	ds_write_b32 v2, v60
	ds_write_b32 v2, v61 offset:16384
	v_add_f32_e32 v63, 1.0, v63
	v_mul_f32_e32 v63, v65, v63
	ds_write_b32 v2, v63 offset:2048
	ds_write_b32 v2, v64 offset:18432
	v_add_f32_e32 v66, 1.0, v66
	v_mul_f32_e32 v66, v68, v66
	ds_write_b32 v2, v66 offset:4096
	ds_write_b32 v2, v67 offset:20480
	v_add_f32_e32 v69, 1.0, v69
	v_mul_f32_e32 v69, v71, v69
	ds_write_b32 v2, v69 offset:6144
	ds_write_b32 v2, v70 offset:22528
	v_add_f32_e32 v72, 1.0, v72
	v_mul_f32_e32 v72, v74, v72
	ds_write_b32 v2, v72 offset:8192
	ds_write_b32 v2, v73 offset:24576
	v_add_f32_e32 v75, 1.0, v75
	v_mul_f32_e32 v75, v77, v75
	ds_write_b32 v2, v75 offset:10240
	ds_write_b32 v2, v76 offset:26624
	v_add_f32_e32 v78, 1.0, v78
	v_mul_f32_e32 v78, v80, v78
	ds_write_b32 v2, v78 offset:12288
	ds_write_b32 v2, v79 offset:28672
	v_add_f32_e32 v81, 1.0, v81
	v_mul_f32_e32 v81, v83, v81
	ds_write_b32 v2, v81 offset:14336
	ds_write_b32 v2, v82 offset:30720
	v_add_u32_e32 v1, 0x1000, v1
	v_add_u32_e32 v2, 0x4000, v2
	s_mov_b64 s[20:21], exec
